# v96 + IN align barrier of the early wave group moved behind its epilogue head (row-stat LDS reads + 8 reductions fill the wait)
# baseline (speedup 1.0000x reference)
; #define PG8_BAR __builtin_amdgcn_s_barrier()
; template <class Epi, bool ALIGN_EPI, bool SP2, bool BF = false, bool HALFM = false, class Order = StaticOrder>
; __device__ __forceinline__ void gemm_phase(LAS unsigned char* lds, const int tid, const Gemm g, const Order& S, const Epi& E, const bool dry = false) {
;     ...
;         if constexpr (ALIGN_EPI) { if (wr == 0) PG8_BAR; }
;         if (!dry) { int fr2 = fr, fq2 = fq; asm volatile("" : "+v"(fr2), "+v"(fq2)); E(acc, cur, wr, wc, fr2, fq2); }
;     __device__ __forceinline__ void operator()(const f32x4 (&acc)[2][2][4][2], const pg8::Unit& u, int wr, int wc, int fr, int fq) const {
;         const int s = u.pn * 4 + wc;
;         if (s >= 53) return;
.Lin_align53:
	s_and_b64 vcc, exec, s[12:13]
	s_cbranch_vccz .LBB0_637
	s_barrier
	s_branch .LBB0_637

; #define PG8_STAGE(bufoff, gbase) do { _Pragma("unroll") for (int _i = 0; _i < 2; ++_i) \
;         __builtin_amdgcn_global_load_lds((const unsigned*)((const char*)(gbase) + voffA[_i]), (LAS unsigned*)(lds + (bufoff) + ldsw + _i * 8192), 16, 0, 0); } while (0)
; #define PG8_LDA(dst, b, h) do { _Pragma("unroll") for (int m = 0; m < 4; ++m) _Pragma("unroll") for (int k = 0; k < 2; ++k) dst[m][k] = *(const LAS h16x8*)(lds + PG8_SA(b, h) + aoff + m * 2048 + k * 1024); } while (0)
; #define PG8_LDB(dst, b, h) do { _Pragma("unroll") for (int n = 0; n < 2; ++n) _Pragma("unroll") for (int k = 0; k < 2; ++k) dst[n][k] = *(const LAS h16x8*)(lds + PG8_SB(b, h) + boff + n * 2048 + k * 1024); } while (0)
; #define PG8_LDA1(dst, b) do { if constexpr (!HALFM) PG8_LDA(dst, b, 1); } while (0)
; #define PG8_MMA1(At, B0, B1) do { if constexpr (!HALFM) { PG8_MMA(1, 0, At, B0); PG8_MMA(1, 1, At, B1); } } while (0)
; #define PG8_WAIT_V(n) asm volatile("s_waitcnt vmcnt(" #n ")" ::: "memory")
; #define PG8_BAR __builtin_amdgcn_s_barrier()
; template <class Epi, bool ALIGN_EPI, bool SP2, bool BF = false, bool HALFM = false, class Order = StaticOrder>
; __device__ __forceinline__ void gemm_phase(LAS unsigned char* lds, const int tid, const Gemm g, const Order& S, const Epi& E, const bool dry = false) {
;     ...
;             PG8_LDB(B0, 0, 0); PG8_LDB(B1, 0, 1); PG8_SCHED; PG8_LDA(At, 0, 0); PG8_STAGE(PG8_SA(1, 1), a1 + hstep);
;             PG8_WAIT_V(8); PG8_WAIT_L(0); PG8_BAR; PG8_MMA(0, 0, At, B0); PG8_MMA(0, 1, At, B1); PG8_BAR; PG8_SCHED;
;             PG8_LDA1(At, 0); PG8_STAGE(PG8_SB(0, 0), b2); PG8_STAGE(PG8_SB(0, 1), b2 + hstep); PG8_STAGE(PG8_SA(0, 0), a2);
;             PG8_WAIT_V(8); PG8_WAIT_L(0); PG8_BAR; PG8_MMA1(At, B0, B1); PG8_BAR; PG8_SCHED;
;             PG8_LDB(B0, 1, 0); PG8_LDB(B1, 1, 1); PG8_SCHED; PG8_LDA(At, 1, 0); PG8_STAGE(PG8_SA(0, 1), a2 + hstep);
;             PG8_WAIT_V(8); PG8_WAIT_L(0); PG8_BAR; PG8_MMA(0, 0, At, B0); PG8_MMA(0, 1, At, B1); PG8_BAR; PG8_SCHED;
;             PG8_LDA1(At, 1); PG8_STAGE(PG8_SB(1, 0), b3); PG8_STAGE(PG8_SB(1, 1), b3 + hstep); PG8_STAGE(PG8_SA(1, 0), a3);
;             PG8_WAIT_V(8); PG8_WAIT_L(0); PG8_BAR; PG8_MMA1(At, B0, B1); PG8_BAR; PG8_SCHED;
;     ...
;         if constexpr (ALIGN_EPI) { if (wr == 0) PG8_BAR; }
;         if (!dry) { int fr2 = fr, fq2 = fq; asm volatile("" : "+v"(fr2), "+v"(fq2)); E(acc, cur, wr, wc, fr2, fq2); }
.Lin_seg4:
	s_mov_b32 m0, s80
	s_add_u32 vcc_lo, s38, 0x80
	s_addc_u32 vcc_hi, s39, 0
	s_add_u32 s38, s38, 0x40080
	ds_read_b128 v[170:173], v199 offset:49152
	ds_read_b128 v[174:177], v199 offset:50176
	ds_read_b128 v[178:181], v199 offset:51200
	ds_read_b128 v[182:185], v199 offset:52224
	ds_read_b128 v[186:189], v199 offset:53248
	ds_read_b128 v[190:193], v199 offset:54272
	ds_read_b128 v[200:203], v199 offset:55296
	ds_read_b128 v[204:207], v199 offset:56320
	global_load_lds_dwordx4 v0, vcc
	s_nop 0
	s_mov_b32 m0, s81
	s_addc_u32 s39, s39, 0
	global_load_lds_dwordx4 v164, vcc
	s_nop 0
	s_mov_b32 m0, s85
	s_nop 0
	global_load_lds_dwordx4 v0, s[38:39]
	s_nop 0
	s_mov_b32 m0, s86
	s_nop 0
	global_load_lds_dwordx4 v164, s[38:39]
	s_add_u32 vcc_lo, s42, 0xfffc0080
	s_addc_u32 vcc_hi, s43, -1
	s_mov_b32 m0, s82
	s_nop 0
	global_load_lds_dwordx4 v0, vcc
	s_nop 0
	s_mov_b32 m0, s83
	s_nop 0
	global_load_lds_dwordx4 v164, vcc
	s_waitcnt vmcnt(8)
	s_waitcnt lgkmcnt(0)
	s_barrier
	s_waitcnt lgkmcnt(0)
	v_mfma_f32_16x16x32_f16 v[30:33], v[132:135], v[170:173], v[30:33]
	v_mfma_f32_16x16x32_f16 v[26:29], v[140:143], v[170:173], v[26:29]
	v_mfma_f32_16x16x32_f16 v[22:25], v[132:135], v[178:181], v[22:25]
	v_mfma_f32_16x16x32_f16 v[18:21], v[140:143], v[178:181], v[18:21]
	v_mfma_f32_16x16x32_f16 v[14:17], v[132:135], v[186:189], v[14:17]
	v_mfma_f32_16x16x32_f16 v[10:13], v[140:143], v[186:189], v[10:13]
	v_mfma_f32_16x16x32_f16 v[6:9], v[132:135], v[200:203], v[6:9]
	v_mfma_f32_16x16x32_f16 v[2:5], v[140:143], v[200:203], v[2:5]
	v_mfma_f32_16x16x32_f16 v[30:33], v[136:139], v[174:177], v[30:33]
	v_mfma_f32_16x16x32_f16 v[26:29], v[144:147], v[174:177], v[26:29]
	v_mfma_f32_16x16x32_f16 v[22:25], v[136:139], v[182:185], v[22:25]
	v_mfma_f32_16x16x32_f16 v[18:21], v[144:147], v[182:185], v[18:21]
	v_mfma_f32_16x16x32_f16 v[14:17], v[136:139], v[190:193], v[14:17]
	v_mfma_f32_16x16x32_f16 v[10:13], v[144:147], v[190:193], v[10:13]
	v_mfma_f32_16x16x32_f16 v[6:9], v[136:139], v[204:207], v[6:9]
	v_mfma_f32_16x16x32_f16 v[2:5], v[144:147], v[204:207], v[2:5]
	v_mfma_f32_16x16x32_f16 v[94:97], v[148:151], v[170:173], v[94:97]
	v_mfma_f32_16x16x32_f16 v[90:93], v[156:159], v[170:173], v[90:93]
	v_mfma_f32_16x16x32_f16 v[86:89], v[148:151], v[178:181], v[86:89]
	v_mfma_f32_16x16x32_f16 v[82:85], v[156:159], v[178:181], v[82:85]
	v_mfma_f32_16x16x32_f16 v[78:81], v[148:151], v[186:189], v[78:81]
	v_mfma_f32_16x16x32_f16 v[74:77], v[156:159], v[186:189], v[74:77]
	v_mfma_f32_16x16x32_f16 v[62:65], v[148:151], v[200:203], v[62:65]
	v_mfma_f32_16x16x32_f16 v[58:61], v[156:159], v[200:203], v[58:61]
	v_mfma_f32_16x16x32_f16 v[94:97], v[152:155], v[174:177], v[94:97]
	v_mfma_f32_16x16x32_f16 v[90:93], v[160:163], v[174:177], v[90:93]
	v_mfma_f32_16x16x32_f16 v[86:89], v[152:155], v[182:185], v[86:89]
	v_mfma_f32_16x16x32_f16 v[82:85], v[160:163], v[182:185], v[82:85]
	v_mfma_f32_16x16x32_f16 v[78:81], v[152:155], v[190:193], v[78:81]
	v_mfma_f32_16x16x32_f16 v[74:77], v[160:163], v[190:193], v[74:77]
	v_mfma_f32_16x16x32_f16 v[62:65], v[152:155], v[204:207], v[62:65]
	v_mfma_f32_16x16x32_f16 v[58:61], v[160:163], v[204:207], v[58:61]
	s_barrier
	s_add_i32 s21, s21, 2
	s_add_u32 s11, s11, 0x100
	s_addc_u32 s19, s19, 0
	s_add_u32 s36, s36, 0x100
	s_addc_u32 s37, s37, 0
	s_cmp_gt_u32 s21, 13
	s_cbranch_scc0 .LBB0_561
	s_and_b64 vcc, exec, s[12:13]
	s_cbranch_vccz .LBB0_564
	s_nop 0

; #define GAS __attribute__((address_space(1)))
;     __device__ __forceinline__ void operator()(const f32x4 (&acc)[2][2][4][2], const pg8::Unit& u, int wr, int wc, int fr, int fq) const {
;     ...
;         const bool lat = u.pm < 128; const int b = lat ? (u.pm >> 3) : (u.pm - 128); const int bb = lat ? b : 16;
;         const int rloc = wr * 64 + fr;
;         const unsigned rbase = (unsigned)u.pm * 256u + (unsigned)rloc;
;         float rs[2][4];
;         { float t[2][4][4];
; #pragma unroll
;           for (int ai = 0; ai < 2; ++ai)
; #pragma unroll
;             for (int m = 0; m < 4; ++m)
; #pragma unroll
;               for (int j = 0; j < 4; ++j) t[ai][m][j] = ldg_f1(ws, (unsigned)WS_ROWSQ + ((unsigned)(4 * fq + j) * (unsigned)MROWS + rbase + ai * 128 + m * 16) * 4u);
; #pragma unroll
;           for (int ai = 0; ai < 2; ++ai)
; #pragma unroll
;             for (int m = 0; m < 4; ++m) rs[ai][m] = __builtin_amdgcn_rsqf(red4((t[ai][m][0] + t[ai][m][1]) + (t[ai][m][2] + t[ai][m][3]), fq * 16 + fr) * (1.f / 1024.f) + EPS); }
;         const bool mapA = s >= 12 && s <= 21;
;         f32x4 bv[2][2];
; #pragma unroll
;         for (int bj = 0; bj < 2; ++bj)
; #pragma unroll
;             for (int n = 0; n < 2; ++n) bv[bj][n] = ldg_f4(ws, shw_off + (unsigned)(bb * NPAD + u.pn * 256 + 128 * bj + 32 * wc + 16 * n + 4 * fq) * 4u);
;     ...
;         const bool isq = s < 20; const float* gv = isq ? gq : gk; const float osc = isq ? QSCALE : 1.f;
;         f32x4 g4[2][2];
; #pragma unroll
;         for (int bj = 0; bj < 2; ++bj)
; #pragma unroll
;             for (int n = 0; n < 2; ++n) g4[bj][n] = *(const GAS f32x4*)(gv + 32 * bj + 16 * n + 4 * fq) * osc;
;         const unsigned pitch = isq ? 512u : 64u;
;         const bool odd = (fr & 1) != 0; const unsigned rpair = (unsigned)(wr * 64 + (fr & ~1)), cb = (odd ? 64u : 0u) + 16u * fq;
;         const unsigned offA = isq ? (unsigned)WS_Q + (((unsigned)u.pm * 256u + rpair) * 512u + (s - 12) * 64) * 2u + cb
;                                   : (unsigned)WS_KB + (((unsigned)(b * 2 + (s - 20)) * NKEY + key0 + rpair) * 64u) * 2u + cb;
.LBB0_569:
	s_and_b64 s[8:9], s[14:15], exec
	s_cselect_b32 s37, 0, s43
	s_cselect_b32 s36, 0, s42
	s_lshl_b32 s19, s4, 8
	s_add_i32 s5, s19, s77
	v_add_u32_e32 v201, s5, v202
	v_lshlrev_b32_e32 v132, 12, v200
	v_lshl_add_u32 v132, v202, 2, v132
	s_lshl_b32 s5, s77, 2
	s_add_i32 s5, s5, 0x24000
	v_add_u32_e32 v132, s5, v132
	ds_read_b32 v133, v132 offset:0
	ds_read_b32 v134, v132 offset:1024
	ds_read_b32 v135, v132 offset:2048
	ds_read_b32 v136, v132 offset:3072
	ds_read_b32 v137, v132 offset:64
	ds_read_b32 v138, v132 offset:1088
	ds_read_b32 v139, v132 offset:2112
	ds_read_b32 v140, v132 offset:3136
	ds_read_b32 v141, v132 offset:128
	ds_read_b32 v142, v132 offset:1152
	ds_read_b32 v143, v132 offset:2176
	ds_read_b32 v144, v132 offset:3200
	ds_read_b32 v145, v132 offset:192
	ds_read_b32 v146, v132 offset:1216
	ds_read_b32 v147, v132 offset:2240
	ds_read_b32 v148, v132 offset:3264
	ds_read_b32 v149, v132 offset:512
	ds_read_b32 v150, v132 offset:1536
	ds_read_b32 v151, v132 offset:2560
	ds_read_b32 v152, v132 offset:3584
	ds_read_b32 v153, v132 offset:576
	ds_read_b32 v154, v132 offset:1600
	ds_read_b32 v155, v132 offset:2624
	ds_read_b32 v156, v132 offset:3648
	ds_read_b32 v157, v132 offset:640
	ds_read_b32 v158, v132 offset:1664
	ds_read_b32 v159, v132 offset:2688
	ds_read_b32 v160, v132 offset:3712
	ds_read_b32 v161, v132 offset:704
	s_lshl_b32 s2, s2, 10
	ds_read_b32 v162, v132 offset:1728
	s_add_i32 s2, s96, s2
	ds_read_b32 v163, v132 offset:2752
	v_lshlrev_b32_e32 v203, 4, v200
	ds_read_b32 v132, v132 offset:3776
	s_add_i32 s2, s3, s2
	s_waitcnt lgkmcnt(0)
	v_add_f32_e32 v133, v133, v134
	v_add_f32_e32 v134, v135, v136
	v_add_f32_e32 v133, v133, v134
	v_mov_b32_e32 v134, v133
	s_nop 1
	v_permlane16_swap_b32_e32 v133, v134
	v_add_f32_e32 v133, v133, v134
	v_mov_b32_e32 v134, v133
	s_nop 1
	v_permlane32_swap_b32_e32 v133, v134
	v_add_f32_e32 v133, v133, v134
	v_fmamk_f32 v133, v133, 0x3a800000, v229
	v_rsq_f32_e32 v176, v133
	v_add_f32_e32 v133, v137, v138
	v_add_f32_e32 v134, v139, v140
	v_add_f32_e32 v133, v133, v134
	v_mov_b32_e32 v134, v133
	s_nop 1
	v_permlane16_swap_b32_e32 v133, v134
	v_add_f32_e32 v133, v133, v134
	v_mov_b32_e32 v134, v133
	s_nop 1
	v_permlane32_swap_b32_e32 v133, v134
	v_add_f32_e32 v133, v133, v134
	v_fmamk_f32 v133, v133, 0x3a800000, v229
	v_rsq_f32_e32 v177, v133
	v_add_f32_e32 v133, v141, v142
	v_add_f32_e32 v134, v143, v144
	v_add_f32_e32 v133, v133, v134
	v_mov_b32_e32 v134, v133
	s_nop 1
	v_permlane16_swap_b32_e32 v133, v134
	v_add_f32_e32 v133, v133, v134
	v_mov_b32_e32 v134, v133
	s_nop 1
	v_permlane32_swap_b32_e32 v133, v134
	v_add_f32_e32 v133, v133, v134
	v_fmamk_f32 v133, v133, 0x3a800000, v229
	s_lshl_b32 s5, s76, 7
	s_add_i32 s5, s5, 0x22400
	v_add_u32_e32 v144, s5, v203
	v_rsq_f32_e32 v174, v133
	v_add_f32_e32 v134, v147, v148
	ds_read_b128 v[136:139], v144
	v_add_f32_e32 v133, v145, v146
	v_add_f32_e32 v133, v133, v134
	v_mov_b32_e32 v134, v133
	s_nop 1
	v_permlane16_swap_b32_e32 v133, v134
	v_add_f32_e32 v133, v133, v134
	v_mov_b32_e32 v134, v133
	s_nop 1
	v_permlane32_swap_b32_e32 v133, v134
	v_add_f32_e32 v133, v133, v134
	v_fmamk_f32 v133, v133, 0x3a800000, v229
	v_rsq_f32_e32 v175, v133
	v_add_f32_e32 v133, v149, v150
	v_add_f32_e32 v134, v151, v152
	v_add_f32_e32 v133, v133, v134
	v_mov_b32_e32 v134, v133
	s_nop 1
	v_permlane16_swap_b32_e32 v133, v134
	v_add_f32_e32 v133, v133, v134
	v_mov_b32_e32 v134, v133
	s_nop 1
	v_permlane32_swap_b32_e32 v133, v134
	v_add_f32_e32 v133, v133, v134
	v_fmamk_f32 v133, v133, 0x3a800000, v229
	v_rsq_f32_e32 v172, v133
	v_add_f32_e32 v133, v153, v154
	v_add_f32_e32 v134, v155, v156
	v_add_f32_e32 v133, v133, v134
	v_mov_b32_e32 v134, v133
	s_nop 1
	v_permlane16_swap_b32_e32 v133, v134
	v_add_f32_e32 v133, v133, v134
	v_mov_b32_e32 v134, v133
	s_nop 1
	v_permlane32_swap_b32_e32 v133, v134
	v_add_f32_e32 v133, v133, v134
	v_fmamk_f32 v133, v133, 0x3a800000, v229
	v_rsq_f32_e32 v173, v133
	v_add_f32_e32 v133, v157, v158
	v_add_f32_e32 v134, v159, v160
	v_add_f32_e32 v133, v133, v134
	v_mov_b32_e32 v134, v133
	s_nop 1
	v_permlane16_swap_b32_e32 v133, v134
	v_add_f32_e32 v133, v133, v134
	v_mov_b32_e32 v134, v133
	s_nop 1
	v_permlane32_swap_b32_e32 v133, v134
	v_add_f32_e32 v133, v133, v134
	v_fmamk_f32 v133, v133, 0x3a800000, v229
	v_rsq_f32_e32 v170, v133
	v_add_f32_e32 v133, v161, v162
	v_add_f32_e32 v132, v163, v132
	v_add_f32_e32 v132, v133, v132
	v_mov_b32_e32 v133, v132
	s_nop 1
	v_permlane16_swap_b32_e32 v132, v133
	v_add_f32_e32 v132, v132, v133
	v_mov_b32_e32 v133, v132
	s_nop 1
	v_permlane32_swap_b32_e32 v132, v133
	v_add_f32_e32 v132, v132, v133
	v_fmamk_f32 v132, v132, 0x3a800000, v229
	v_rsq_f32_e32 v171, v132
	ds_read_b128 v[132:135], v144 offset:64
	s_and_b32 s2, s19, 0x700
	ds_read_b128 v[140:143], v144 offset:512
	s_add_i32 s5, s2, 0x100
	ds_read_b128 v[144:147], v144 offset:576
	s_waitcnt lgkmcnt(0)
	s_and_b64 vcc, exec, s[12:13]
	s_cbranch_vccz .Lin_noalign
	s_barrier
.Lin_noalign:
	s_and_b64 s[2:3], s[38:39], exec
	s_cselect_b32 s97, s5, 0
	s_sub_i32 s8, s11, 22
	s_mov_b64 s[2:3], -1
	s_cmp_gt_u32 s8, -11
	s_cbranch_scc0 .LBB0_592
	s_cmp_lt_u32 s78, 20
	s_cselect_b64 s[2:3], -1, 0
	v_readlane_b32 s56, v252, 28
	s_and_b64 s[42:43], s[2:3], exec
	v_readlane_b32 s60, v252, 32
	v_readlane_b32 s62, v252, 34
	v_readlane_b32 s61, v252, 33
	v_readlane_b32 s63, v252, 35
	s_cselect_b32 s9, s60, s62
	v_lshlrev_b32_e32 v186, 2, v200
	s_cselect_b32 s5, s61, s63
	s_add_u32 s42, s9, s16
	s_addc_u32 s43, s5, s17
	v_ashrrev_i32_e32 v187, 31, v186
	v_lshl_add_u64 v[148:149], v[186:187], 2, s[42:43]
	global_load_dwordx4 v[160:163], v[148:149], off
	global_load_dwordx4 v[156:159], v[148:149], off offset:64
	global_load_dwordx4 v[152:155], v[148:149], off offset:128
	s_nop 0
	global_load_dwordx4 v[148:151], v[148:149], off offset:192
	v_and_b32_e32 v178, -2, v202
	s_cmp_gt_u32 s78, 19
	v_add_u32_e32 v178, s77, v178
	s_mov_b64 s[42:43], -1
	v_readlane_b32 s57, v252, 29
	v_readlane_b32 s58, v252, 30
	v_readlane_b32 s59, v252, 31
	v_readlane_b32 s64, v252, 36
	v_readlane_b32 s65, v252, 37
	v_readlane_b32 s66, v252, 38
	v_readlane_b32 s67, v252, 39
	v_readlane_b32 s68, v252, 40
	v_readlane_b32 s69, v252, 41
	v_readlane_b32 s70, v252, 42
	v_readlane_b32 s71, v252, 43
	s_cbranch_scc0 .LBB0_572
	s_lshl_b32 s5, s21, 1
	s_add_i32 s5, s11, s5
	s_mulk_i32 s5, 0x900
	s_add_i32 s5, s5, s97
	s_add_i32 s5, s5, 0xffff4c00
	v_add_u32_e32 v179, s5, v178
	v_mov_b32_e32 v180, 0x10380000
	v_lshl_add_u32 v187, v179, 7, v180
	s_mov_b64 s[42:43], 0
